# barrier audit: workspace overlays need the device-wide rendezvous after down1 (both layers) and after W_out (layer 0); those barriers are full again; 9 of 18 per-layer barriers stay XCD-local
# baseline (speedup 1.0000x reference)
; __device__ __forceinline__ unsigned xb_add(unsigned* p, unsigned v) { return __hip_atomic_fetch_add(p, v, __ATOMIC_RELAXED, __HIP_MEMORY_SCOPE_AGENT); }
; __device__ __forceinline__ void xcd_barrier(const XcdBarrier& b) {
;     ...
;     if (threadIdx.x == 0) {
;         unsigned* bar = b.bar;
;         __builtin_amdgcn_s_waitcnt(0);
;         unsigned nloc = b.st[0], nx = b.st[1];
;         if (nloc == 0u) { xcd_barrier_complete(bar, b.x, nloc, nx); b.st[0] = nloc; b.st[1] = nx; }
;         const unsigned old = xb_add(&bar[XB_XSUB(b.x)], 1u);
;         const unsigned gen = old / nloc;
;         if (old + 1u == (gen + 1u) * nloc) {
;             __builtin_amdgcn_fence(__ATOMIC_RELEASE, "agent");
;             asm volatile("s_waitcnt vmcnt(0)" ::: "memory");
;             const unsigned og = xb_add(&bar[XB_TOP], 1u);
.LBB0_1449:
	s_andn2_saveexec_b64 s[6:7], s[6:7]
	s_cbranch_execz .LBB0_1469
	v_mov_b32_e32 v1, 0x26a3c
	ds_read_b32 v1, v1
	s_waitcnt lgkmcnt(0)
	v_cmp_ne_u32_e32 vcc, 0, v1
	s_cbranch_vccnz .Lxcd_local_3
	s_mov_b64 s[6:7], exec
	buffer_wbl2 sc1
	s_waitcnt lgkmcnt(0)
	s_waitcnt vmcnt(0)
	v_mbcnt_lo_u32_b32 v1, s6, 0
	v_mbcnt_hi_u32_b32 v1, s7, v1
	v_cmp_eq_u32_e32 vcc, 0, v1
	s_and_saveexec_b64 s[8:9], vcc
	s_cbranch_execz .LBB0_1452
	s_bcnt1_i32_b64 s4, s[6:7]
	v_readlane_b32 s6, v253, 38
	v_mov_b32_e32 v3, s4
	v_readlane_b32 s7, v253, 39
	s_nop 4
	global_atomic_add v3, v99, v3, s[6:7] sc0

; __device__ __forceinline__ unsigned xb_add(unsigned* p, unsigned v) { return __hip_atomic_fetch_add(p, v, __ATOMIC_RELAXED, __HIP_MEMORY_SCOPE_AGENT); }
; __device__ __forceinline__ void xcd_barrier(const XcdBarrier& b) {
;     asm volatile("s_waitcnt vmcnt(0)" ::: "memory");
;     __syncthreads();
;     if (threadIdx.x == 0) {
;         unsigned* bar = b.bar;
;         __builtin_amdgcn_s_waitcnt(0);
;         unsigned nloc = b.st[0], nx = b.st[1];
;         if (nloc == 0u) { xcd_barrier_complete(bar, b.x, nloc, nx); b.st[0] = nloc; b.st[1] = nx; }
;         const unsigned old = xb_add(&bar[XB_XSUB(b.x)], 1u);
.LBB0_1877:
	v_mov_b32_e32 v4, 0x26a38
	ds_read_b32 v5, v4
	s_waitcnt lgkmcnt(0)
	ds_write_b32 v4, v5 offset:4
	v_readlane_b32 s1, v255, 21
	s_waitcnt vmcnt(0) expcnt(0) lgkmcnt(0)
	s_nop 0
	v_mov_b32_e32 v1, s1
	ds_read_b32 v3, v1
	v_readlane_b32 s1, v255, 22
	s_waitcnt lgkmcnt(0)
	v_cmp_ne_u32_e32 vcc, 0, v3
	v_mov_b32_e32 v1, s1
	ds_read_b32 v2, v1
	s_cbranch_vccnz .LBB0_1892
	s_mov_b32 s4, 1
	s_branch .LBB0_1880
